# gla_out loop loads issued one row ahead; plus phase 0/4 reorders, hand-written QK-norm/RoPE, GLA+attention LDS pipelining
# speedup vs baseline: 1.0047x; 1.0047x over previous
; __device__ __forceinline__ void gla_out_phase(const Params& P) {
;     const int tid = threadIdx.x, lane = tid & 63, wave = tid >> 6;
;     const bf16_t* proj = (const bf16_t*)(P.ws + WS_PROJ);
;     const float* of = (const float*)(P.ws + WS_X); const float* ob = of + (size_t)NTOK * 1024;
;     bf16_t* mix = (bf16_t*)(P.ws + WS_MIX);
;     const f32x4 gn = *(const f32x4*)(P.in[18] + lane * 4);
;     for (int idx = blockIdx.x * 8 + wave; idx < NTOK * 4; idx += gridDim.x * 8) {
;         const int row = idx >> 2, h = idx & 3; const size_t off = (size_t)row * 1024 + h * 256 + lane * 4;
;         const f32x4 o = *(const f32x4*)(of + off) + *(const f32x4*)(ob + off);
.LBB0_625:
	s_cmp_lt_i32 s24, 6
	s_cselect_b64 s[6:7], -1, 0
	s_and_b64 s[0:1], s[6:7], s[0:1]
	s_andn2_b64 vcc, exec, s[0:1]
	s_cbranch_vccnz .LBB0_630
	v_lshrrev_b32_e32 v6, 6, v224
	v_lshl_add_u32 v5, s22, 3, v6
	s_mov_b32 s0, 0x10000
	v_cmp_gt_i32_e32 vcc, s0, v5
	s_and_saveexec_b64 s[8:9], vcc
	s_cbranch_execz .LBB0_629
	v_lshlrev_b32_e32 v0, 2, v224
	s_waitcnt lgkmcnt(0)
	v_and_b32_e32 v4, 0xfc, v0
	v_lshlrev_b32_e32 v0, 2, v4
	global_load_dwordx4 v[0:3], v0, s[40:41]
	v_mbcnt_lo_u32_b32 v8, -1, 0
	v_mbcnt_hi_u32_b32 v8, -1, v8
	v_and_b32_e32 v9, 64, v8
	v_add_u32_e32 v9, 64, v9
	v_xor_b32_e32 v10, 1, v8
	v_cmp_lt_i32_e32 vcc, v10, v9
	s_add_u32 s10, s50, 0xf418000
	v_mov_b32_e32 v7, 0
	v_cndmask_b32_e32 v10, v8, v10, vcc
	v_lshlrev_b32_e32 v12, 2, v10
	v_xor_b32_e32 v10, 2, v8
	v_cmp_lt_i32_e32 vcc, v10, v9
	v_lshlrev_b32_e32 v6, 8, v6
	s_addc_u32 s11, s51, 0
	v_cndmask_b32_e32 v10, v8, v10, vcc
	v_lshlrev_b32_e32 v13, 2, v10
	v_xor_b32_e32 v10, 4, v8
	v_cmp_lt_i32_e32 vcc, v10, v9
	s_lshl_b32 s14, s26, 3
	v_lshl_add_u32 v18, s22, 11, v6
	v_cndmask_b32_e32 v10, v8, v10, vcc
	v_lshlrev_b32_e32 v14, 2, v10
	v_xor_b32_e32 v10, 8, v8
	v_cmp_lt_i32_e32 vcc, v10, v9
	s_lshl_b32 s15, s26, 11
	s_mov_b64 s[12:13], 0
	v_cndmask_b32_e32 v10, v8, v10, vcc
	v_lshlrev_b32_e32 v15, 2, v10
	v_xor_b32_e32 v10, 16, v8
	v_cmp_lt_i32_e32 vcc, v10, v9
	v_mov_b32_e32 v19, 0x358637bd
	s_mov_b32 s16, 0x800000
	v_cndmask_b32_e32 v10, v8, v10, vcc
	v_lshlrev_b32_e32 v16, 2, v10
	v_xor_b32_e32 v10, 32, v8
	v_cmp_lt_i32_e32 vcc, v10, v9
	s_movk_i32 s17, 0x2600
	v_mov_b32_e32 v11, v7
	v_cndmask_b32_e32 v8, v8, v10, vcc
	v_lshlrev_b32_e32 v17, 2, v8
	v_mov_b64_e32 v[8:9], s[50:51]
	v_lshlrev_b32_e32 v10, 1, v4
	s_mov_b32 s18, 0x1bc19000
	s_movk_i32 s19, 0xea00
	s_mov_b32 s20, 0xffff
	v_mov_b32_e32 v87, v7
	v_ashrrev_i32_e32 v68, 2, v5
	v_ashrrev_i32_e32 v69, 31, v68
	v_and_b32_e32 v76, 0x300, v18
	v_mad_i64_i32 v[70:71], s[0:1], v68, s17, v[8:9]
	v_lshlrev_b64 v[72:73], 10, v[68:69]
	v_lshlrev_b32_e32 v86, 1, v76
	v_mad_i64_i32 v[68:69], s[0:1], v68, s19, v[70:71]
	v_or_b32_e32 v72, v72, v76
	v_add_u32_e32 v5, s14, v5
	v_lshl_add_u64 v[74:75], v[70:71], 0, v[86:87]
	v_lshl_add_u64 v[68:69], v[68:69], 0, v[86:87]
	v_or_b32_e32 v72, v72, v4
	v_cmp_lt_i32_e32 vcc, s20, v5
	v_lshl_add_u64 v[70:71], v[74:75], 0, v[10:11]
	v_lshl_add_u64 v[78:79], v[68:69], 0, v[10:11]
	v_lshlrev_b64 v[68:69], 2, v[72:73]
	s_or_b64 s[12:13], vcc, s[12:13]
	v_add_co_u32_e32 v76, vcc, s18, v70
	v_lshl_add_u64 v[80:81], s[36:37], 0, v[68:69]
	s_nop 0
	v_addc_co_u32_e32 v77, vcc, 0, v71, vcc
	v_lshl_add_u64 v[82:83], s[10:11], 0, v[68:69]
	global_load_dwordx4 v[68:71], v[80:81], off
	global_load_dwordx4 v[72:75], v[82:83], off
	global_load_dwordx2 v[84:85], v[76:77], off offset:3072
	v_add_u32_e32 v18, s15, v18
; __device__ __forceinline__ unsigned cvt_pk_bf16(float lo, float hi) { const f32x2 v = {lo, hi}; const bf16v2_t b = __builtin_convertvector(v, bf16v2_t); return __builtin_bit_cast(unsigned, b); }
; __device__ __forceinline__ float silu_f(float x) { return x / (1.f + __expf(-x)); }
; __device__ __forceinline__ void gla_out_phase(const Params& P) {
;     ...
;     for (int idx = blockIdx.x * 8 + wave; idx < NTOK * 4; idx += gridDim.x * 8) {
;         const int row = idx >> 2, h = idx & 3; const size_t off = (size_t)row * 1024 + h * 256 + lane * 4;
;         const f32x4 o = *(const f32x4*)(of + off) + *(const f32x4*)(ob + off);
;         const float ss = wave_sum((o[0] * o[0] + o[1] * o[1]) + (o[2] * o[2] + o[3] * o[3]));
;         const float rstd = rsqrtf(ss * (1.f / 256.f) + 1e-6f);
;         const u32x2 gw = *(const u32x2*)(proj + (size_t)row * INCP + C_BG + h * 256 + lane * 4);
;         const float g0 = __uint_as_float(gw.x << 16), g1 = __uint_as_float(gw.x & 0xffff0000u), g2 = __uint_as_float(gw.y << 16), g3 = __uint_as_float(gw.y & 0xffff0000u);
;         u32x2 w; w.x = cvt_pk_bf16(o[0] * rstd * gn[0] * silu_f(g0), o[1] * rstd * gn[1] * silu_f(g1)); w.y = cvt_pk_bf16(o[2] * rstd * gn[2] * silu_f(g2), o[3] * rstd * gn[3] * silu_f(g3));
;         *(u32x2*)(mix + (size_t)row * D + 1024 + h * 256 + lane * 4) = w;
.LBB0_628:
	s_waitcnt vmcnt(0)
	v_mov_b32_e32 v20, v68
	v_mov_b32_e32 v21, v69
	v_mov_b32_e32 v22, v70
	v_mov_b32_e32 v23, v71
	v_mov_b32_e32 v24, v72
	v_mov_b32_e32 v25, v73
	v_mov_b32_e32 v26, v74
	v_mov_b32_e32 v27, v75
	v_mov_b32_e32 v36, v84
	v_mov_b32_e32 v37, v85
	v_mov_b32_e32 v30, v78
	v_mov_b32_e32 v31, v79
	v_ashrrev_i32_e32 v68, 2, v5
	v_ashrrev_i32_e32 v69, 31, v68
	v_and_b32_e32 v76, 0x300, v18
	v_mad_i64_i32 v[70:71], s[0:1], v68, s17, v[8:9]
	v_lshlrev_b64 v[72:73], 10, v[68:69]
	v_lshlrev_b32_e32 v86, 1, v76
	v_mad_i64_i32 v[68:69], s[0:1], v68, s19, v[70:71]
	v_or_b32_e32 v72, v72, v76
	v_add_u32_e32 v5, s14, v5
	v_lshl_add_u64 v[74:75], v[70:71], 0, v[86:87]
	v_lshl_add_u64 v[68:69], v[68:69], 0, v[86:87]
	v_or_b32_e32 v72, v72, v4
	v_cmp_lt_i32_e32 vcc, s20, v5
	v_lshl_add_u64 v[70:71], v[74:75], 0, v[10:11]
	v_lshl_add_u64 v[78:79], v[68:69], 0, v[10:11]
	v_lshlrev_b64 v[68:69], 2, v[72:73]
	s_mov_b64 s[98:99], vcc
	v_add_co_u32_e32 v76, vcc, s18, v70
	v_lshl_add_u64 v[80:81], s[36:37], 0, v[68:69]
	s_nop 0
	v_addc_co_u32_e32 v77, vcc, 0, v71, vcc
	v_lshl_add_u64 v[82:83], s[10:11], 0, v[68:69]
	global_load_dwordx4 v[68:71], v[80:81], off
	global_load_dwordx4 v[72:75], v[82:83], off
	global_load_dwordx2 v[84:85], v[76:77], off offset:3072
	v_add_u32_e32 v18, s15, v18
	v_pk_add_f32 v[22:23], v[22:23], v[26:27]
	v_lshlrev_b32_e32 v6, 16, v36
	v_and_b32_e32 v36, 0xffff0000, v36
	v_lshlrev_b32_e32 v38, 16, v37
	v_and_b32_e32 v37, 0xffff0000, v37
	v_mul_f32_e32 v28, 0xbfb8aa3b, v6
	v_mul_f32_e32 v29, 0xbfb8aa3b, v36
	v_mul_f32_e32 v32, 0xbfb8aa3b, v38
	v_mul_f32_e32 v33, 0xbfb8aa3b, v37
	v_pk_add_f32 v[20:21], v[20:21], v[24:25]
	v_exp_f32_e32 v24, v28
	v_exp_f32_e32 v25, v29
	v_exp_f32_e32 v26, v32
	v_exp_f32_e32 v27, v33
	v_pk_mul_f32 v[28:29], v[22:23], v[22:23]
	v_pk_mul_f32 v[32:33], v[20:21], v[20:21]
	v_pk_add_f32 v[24:25], v[24:25], 1.0 op_sel_hi:[1,0]
	v_pk_mov_b32 v[34:35], v[32:33], v[28:29] op_sel:[1,0]
	v_mov_b32_e32 v33, v29
	v_pk_add_f32 v[28:29], v[34:35], v[32:33]
	v_pk_add_f32 v[26:27], v[26:27], 1.0 op_sel_hi:[1,0]
	v_add_f32_e32 v28, v28, v29
	ds_bpermute_b32 v29, v12, v28
	v_div_scale_f32 v32, s[0:1], v25, v25, v36
	v_div_scale_f32 v34, s[0:1], v24, v24, v6
	v_div_scale_f32 v39, s[2:3], v27, v27, v37
	v_rcp_f32_e32 v43, v32
	v_rcp_f32_e32 v44, v34
	v_rcp_f32_e32 v45, v39
	v_div_scale_f32 v41, s[4:5], v26, v26, v38
	s_waitcnt lgkmcnt(0)
	v_add_f32_e32 v28, v28, v29
	v_rcp_f32_e32 v46, v41
	v_fma_f32 v29, -v32, v43, 1.0
	v_fma_f32 v47, -v34, v44, 1.0
	v_fma_f32 v48, -v39, v45, 1.0
	ds_bpermute_b32 v50, v13, v28
	v_div_scale_f32 v33, vcc, v36, v25, v36
	v_div_scale_f32 v35, s[0:1], v6, v24, v6
	v_div_scale_f32 v40, s[2:3], v37, v27, v37
	v_fmac_f32_e32 v43, v29, v43
	v_fmac_f32_e32 v44, v47, v44
	v_fmac_f32_e32 v45, v48, v45
	v_mul_f32_e32 v29, v33, v43
	v_mul_f32_e32 v47, v35, v44
	v_mul_f32_e32 v48, v40, v45
	v_fma_f32 v51, -v32, v29, v33
	v_fma_f32 v52, -v34, v47, v35
	v_fma_f32 v53, -v39, v48, v40
	v_fma_f32 v49, -v41, v46, 1.0
	v_fmac_f32_e32 v29, v51, v43
	v_fmac_f32_e32 v47, v52, v44
	v_fmac_f32_e32 v48, v53, v45
	v_div_scale_f32 v42, s[4:5], v38, v26, v38
	v_fmac_f32_e32 v46, v49, v46
	v_fma_f32 v32, -v32, v29, v33
	v_fma_f32 v33, -v34, v47, v35
	v_fma_f32 v34, -v39, v48, v40
	s_waitcnt lgkmcnt(0)
	v_add_f32_e32 v39, v28, v50
	v_mul_f32_e32 v49, v42, v46
	v_div_fmas_f32 v28, v32, v43, v29
	ds_bpermute_b32 v32, v14, v39
	v_fma_f32 v54, -v41, v49, v42
	s_mov_b64 vcc, s[0:1]
	v_fmac_f32_e32 v49, v54, v46
	v_div_fixup_f32 v25, v28, v25, v36
	v_div_fmas_f32 v28, v33, v44, v47
	s_mov_b64 vcc, s[2:3]
	v_fma_f32 v35, -v41, v49, v42
	v_div_fixup_f32 v24, v28, v24, v6
	v_div_fmas_f32 v6, v34, v45, v48
	s_mov_b64 vcc, s[4:5]
	v_div_fixup_f32 v27, v6, v27, v37
	v_div_fmas_f32 v6, v35, v46, v49
	v_div_fixup_f32 v26, v6, v26, v38
	s_waitcnt lgkmcnt(0)
	v_add_f32_e32 v6, v39, v32
	v_add_co_u32_e32 v28, vcc, 0x17c18000, v30
	ds_bpermute_b32 v30, v15, v6
	s_nop 0
	v_addc_co_u32_e32 v29, vcc, 0, v31, vcc
	s_waitcnt lgkmcnt(0)
	v_add_f32_e32 v6, v6, v30
	ds_bpermute_b32 v30, v16, v6
	s_waitcnt lgkmcnt(0)
	v_add_f32_e32 v6, v6, v30
	ds_bpermute_b32 v30, v17, v6
	s_waitcnt lgkmcnt(0)
	v_add_f32_e32 v6, v6, v30
	v_fmamk_f32 v6, v6, 0x3b800000, v19
	v_mul_f32_e32 v30, 0x4b800000, v6
	v_cmp_gt_f32_e32 vcc, s16, v6
	s_nop 1
	v_cndmask_b32_e32 v6, v6, v30, vcc
	v_rsq_f32_e32 v6, v6
	s_nop 0
	v_mul_f32_e32 v30, 0x45800000, v6
	v_cndmask_b32_e32 v6, v6, v30, vcc
	v_pk_mul_f32 v[20:21], v[20:21], v[6:7] op_sel_hi:[1,0]
	v_pk_mul_f32 v[22:23], v[22:23], v[6:7] op_sel_hi:[1,0]
	v_pk_mul_f32 v[20:21], v[0:1], v[20:21]
	v_pk_mul_f32 v[22:23], v[2:3], v[22:23]
	v_pk_mul_f32 v[20:21], v[24:25], v[20:21]
	v_pk_mul_f32 v[22:23], v[26:27], v[22:23]
	v_cvt_pk_bf16_f32 v20, v20, v21
	v_cvt_pk_bf16_f32 v21, v22, v23
	global_store_dwordx2 v[28:29], v[20:21], off offset:2048
	s_andn2_b64 exec, exec, s[12:13]
	s_or_b64 s[12:13], s[12:13], s[98:99]
	s_cbranch_execnz .LBB0_628
